# attention item order: waves 0-3 take NSA tiles at their rank position, waves 4-7 at the mirrored position in every quarter (per-SIMD pair balance)
# baseline (speedup 1.0000x reference)
; __device__ __forceinline__ void attention_phase(const Ctx& C) {
;     const int bxx = C.gw / NWAVES; const bool xmode = (C.G & 7) == 0;
;     const int x = bxx & 7, rank = xmode ? (bxx >> 3) * NWAVES + C.wave : C.gw, nrank = xmode ? (C.G >> 3) * NWAVES : C.NGW, nitem = xmode ? 1536 : 12288;
;     const int nper = (nitem + nrank - 1) / nrank, nmem_it = xmode ? (512 + nrank - 1) / nrank : 0; const bool flip = xmode && (nitem % nrank == 0); const int rot = flip ? ((C.wave * 3) >> 3) * 2 : 0;
;     for (int k0 = 0; k0 < nper; ++k0) {
;         const int kk = flip ? (k0 + rot) % nper : k0; const int i = rank + kk * nrank; if (i >= nitem) continue;
;         int nsa_n, mem_e;
;         if (xmode) { nsa_n = (i < 1024) ? (x >> 1) * 2048 + 2 * i + (x & 1) : -1; mem_e = x * 512 + (i - 1024); }
;         else { if (i < 8192) { const int k = i >> 11, w = i & 2047; nsa_n = k * 2048 + ((k & 1) ? 2047 - w : w); } else nsa_n = -1; mem_e = i - 8192; }
;         if (nsa_n >= 0) { const int k = nsa_n >> 11; nsa_tile(C, k >> 1, k & 1, (nsa_n & 2047) * 8); }
.LBB0_653:
	s_mul_i32 s3, s0, s26
	s_sub_i32 s2, s26, s9
	s_add_i32 s2, s2, -1
	s_xor_b32 s2, s2, 7
	s_bitcmp1_b32 s9, 2
	s_cselect_b32 s2, s2, s9
	s_cmp_lt_u32 s0, 4
	s_cselect_b32 s2, s2, s9
	s_add_i32 s3, s3, s2
	s_cmp_ge_i32 s3, s47
	s_cbranch_scc1 .LBB0_650
	s_mov_b64 s[0:1], -1
	s_and_b64 vcc, exec, s[50:51]
	s_cbranch_vccz .LBB0_661
	s_and_b32 s0, s3, 0x7ff
	s_and_b32 s1, s3, 0xfffff800
	s_and_b32 s2, s3, 0x800
	s_xor_b32 s4, s0, 0x7ff
	s_cmp_eq_u32 s2, 0
	s_cselect_b32 s0, s0, s4
	s_or_b32 s0, s0, s1
	s_cmpk_lt_i32 s3, 0x2000
	s_cselect_b32 s2, s0, -1
	s_add_i32 s5, s3, 0xffffe000
	s_cbranch_execz .LBB0_662
